# hot loop heads (4 GEMM K loops, attention main loop) aligned to 64 bytes
# speedup vs baseline: 1.0050x; 1.0050x over previous
.LBB0_300:
	s_ashr_i32 s45, s44, 31
	s_lshl_b64 s[10:11], s[44:45], 20
	s_add_u32 s46, s7, s10
	s_addc_u32 s47, s8, s11
	s_and_b64 s[10:11], s[40:41], exec
	s_cselect_b32 s45, s47, s55
	s_cselect_b32 s69, s46, s54
	s_ashr_i32 s43, s42, 31
	s_lshl_b64 s[10:11], s[42:43], 20
	s_add_u32 s48, s9, s10
	s_addc_u32 s49, s52, s11
	s_and_b64 s[10:11], s[40:41], exec
	s_cselect_b32 s43, s49, s21
	s_cselect_b32 s70, s48, s20
	s_add_u32 s71, s20, 0x10000
	s_addc_u32 s72, s21, 0
	s_add_u32 s54, s54, 0x80080
	v_mov_b32_e32 v2, 0
	s_addc_u32 s55, s55, 0
	s_mov_b32 s73, -2
	v_mov_b32_e32 v3, v2
	v_mov_b32_e32 v4, v2
	v_mov_b32_e32 v5, v2
	v_mov_b32_e32 v6, v2
	v_mov_b32_e32 v7, v2
	v_mov_b32_e32 v8, v2
	v_mov_b32_e32 v9, v2
	v_mov_b32_e32 v10, v2
	v_mov_b32_e32 v11, v2
	v_mov_b32_e32 v12, v2
	v_mov_b32_e32 v13, v2
	v_mov_b32_e32 v18, v2
	v_mov_b32_e32 v19, v2
	v_mov_b32_e32 v20, v2
	v_mov_b32_e32 v21, v2
	v_mov_b32_e32 v26, v2
	v_mov_b32_e32 v27, v2
	v_mov_b32_e32 v28, v2
	v_mov_b32_e32 v29, v2
	v_mov_b32_e32 v34, v2
	v_mov_b32_e32 v35, v2
	v_mov_b32_e32 v36, v2
	v_mov_b32_e32 v37, v2
	v_mov_b32_e32 v42, v2
	v_mov_b32_e32 v43, v2
	v_mov_b32_e32 v44, v2
	v_mov_b32_e32 v45, v2
	v_mov_b32_e32 v50, v2
	v_mov_b32_e32 v51, v2
	v_mov_b32_e32 v52, v2
	v_mov_b32_e32 v53, v2
	v_mov_b32_e32 v14, v2
	v_mov_b32_e32 v15, v2
	v_mov_b32_e32 v16, v2
	v_mov_b32_e32 v17, v2
	v_mov_b32_e32 v22, v2
	v_mov_b32_e32 v23, v2
	v_mov_b32_e32 v24, v2
	v_mov_b32_e32 v25, v2
	v_mov_b32_e32 v30, v2
	v_mov_b32_e32 v31, v2
	v_mov_b32_e32 v32, v2
	v_mov_b32_e32 v33, v2
	v_mov_b32_e32 v38, v2
	v_mov_b32_e32 v39, v2
	v_mov_b32_e32 v40, v2
	v_mov_b32_e32 v41, v2
	v_mov_b32_e32 v46, v2
	v_mov_b32_e32 v47, v2
	v_mov_b32_e32 v48, v2
	v_mov_b32_e32 v49, v2
	v_mov_b32_e32 v54, v2
	v_mov_b32_e32 v55, v2
	v_mov_b32_e32 v56, v2
	v_mov_b32_e32 v57, v2
	v_mov_b32_e32 v58, v2
	v_mov_b32_e32 v59, v2
	v_mov_b32_e32 v60, v2
	v_mov_b32_e32 v61, v2
	v_mov_b32_e32 v62, v2
	v_mov_b32_e32 v63, v2
	v_mov_b32_e32 v64, v2
	v_mov_b32_e32 v65, v2
	v_mov_b32_e32 v66, v2
	v_mov_b32_e32 v67, v2
	v_mov_b32_e32 v68, v2
	v_mov_b32_e32 v69, v2
	v_mov_b32_e32 v70, v2
	v_mov_b32_e32 v71, v2
	v_mov_b32_e32 v72, v2
	v_mov_b32_e32 v73, v2
	v_mov_b32_e32 v74, v2
	v_mov_b32_e32 v75, v2
	v_mov_b32_e32 v76, v2
	v_mov_b32_e32 v77, v2
	v_mov_b32_e32 v82, v2
	v_mov_b32_e32 v83, v2
	v_mov_b32_e32 v84, v2
	v_mov_b32_e32 v85, v2
	v_mov_b32_e32 v90, v2
	v_mov_b32_e32 v91, v2
	v_mov_b32_e32 v92, v2
	v_mov_b32_e32 v93, v2
	v_mov_b32_e32 v100, v2
	v_mov_b32_e32 v101, v2
	v_mov_b32_e32 v102, v2
	v_mov_b32_e32 v103, v2
	v_mov_b32_e32 v108, v2
	v_mov_b32_e32 v109, v2
	v_mov_b32_e32 v110, v2
	v_mov_b32_e32 v111, v2
	v_mov_b32_e32 v116, v2
	v_mov_b32_e32 v117, v2
	v_mov_b32_e32 v118, v2
	v_mov_b32_e32 v119, v2
	v_mov_b32_e32 v78, v2
	v_mov_b32_e32 v79, v2
	v_mov_b32_e32 v80, v2
	v_mov_b32_e32 v81, v2
	v_mov_b32_e32 v86, v2
	v_mov_b32_e32 v87, v2
	v_mov_b32_e32 v88, v2
	v_mov_b32_e32 v89, v2
	v_mov_b32_e32 v94, v2
	v_mov_b32_e32 v95, v2
	v_mov_b32_e32 v96, v2
	v_mov_b32_e32 v97, v2
	v_mov_b32_e32 v104, v2
	v_mov_b32_e32 v105, v2
	v_mov_b32_e32 v106, v2
	v_mov_b32_e32 v107, v2
	v_mov_b32_e32 v112, v2
	v_mov_b32_e32 v113, v2
	v_mov_b32_e32 v114, v2
	v_mov_b32_e32 v115, v2
	v_mov_b32_e32 v120, v2
	v_mov_b32_e32 v121, v2
	v_mov_b32_e32 v122, v2
	v_mov_b32_e32 v123, v2
	v_mov_b32_e32 v124, v2
	v_mov_b32_e32 v125, v2
	v_mov_b32_e32 v126, v2
	v_mov_b32_e32 v127, v2
	v_mov_b32_e32 v128, v2
	v_mov_b32_e32 v129, v2
	v_mov_b32_e32 v130, v2
	v_mov_b32_e32 v131, v2
	s_cmp_eq_u32 s100, 1
	s_cbranch_scc1 .Lgi_h0_loop
	s_cmp_eq_u32 s100, 2
	s_cbranch_scc1 .Lgi_h1_loop
	.p2align	6

.LBB0_452:
	s_bfe_u32 s7, s4, 0x20001
	s_lshl_b32 s5, s6, 8
	s_and_b32 s8, s4, 1
	s_lshl_b32 s4, s7, 12
	s_and_b32 s5, s5, 0xf00
	s_or_b32 s81, s4, s5
	s_lshl_b32 s4, s81, 11
	s_add_u32 s9, s68, s4
	s_addc_u32 s10, s69, 0
	s_lshl_b32 s5, s6, 3
	s_lshl_b32 s4, s8, 9
	s_and_b32 s5, s5, 0xffffff80
	s_add_i32 s4, s5, s4
	s_ashr_i32 s5, s4, 31
	s_lshl_b64 s[48:49], s[4:5], 1
	s_add_u32 s20, s9, s48
	s_addc_u32 s21, s10, s49
	s_mul_i32 s6, s7, 0x220000
	s_add_u32 s4, s71, s6
	s_addc_u32 s5, s72, 0
	s_lshl_b32 s8, s8, 8
	s_add_u32 s4, s4, s8
	v_mov_b32_e32 v76, v0
	s_addc_u32 s5, s5, 0
	s_add_u32 s6, s73, s6
	v_ashrrev_i32_e32 v18, 4, v76
	v_lshlrev_b32_e32 v24, 3, v76
	v_add_u32_e32 v20, 32, v18
	s_addc_u32 s9, s74, 0
	v_and_b32_e32 v2, 0x78, v24
	v_ashrrev_i32_e32 v19, 31, v18
	v_ashrrev_i32_e32 v21, 31, v20
	s_add_u32 s36, s6, s8
	v_lshlrev_b32_e32 v25, 1, v2
	v_lshlrev_b64 v[50:51], 9, v[18:19]
	v_lshlrev_b64 v[10:11], 9, v[20:21]
	s_addc_u32 s37, s9, 0
	v_or_b32_e32 v52, v50, v25
	v_mov_b32_e32 v53, v51
	v_or_b32_e32 v10, v10, v25
	v_lshl_add_u64 v[2:3], s[36:37], 0, v[52:53]
	v_lshl_add_u64 v[6:7], s[36:37], 0, v[10:11]
	v_lshl_add_u64 v[12:13], s[4:5], 0, v[52:53]
	v_lshl_add_u64 v[14:15], s[4:5], 0, v[10:11]
	global_load_dwordx4 v[2:5], v[2:3], off
	s_nop 0
	global_load_dwordx4 v[6:9], v[6:7], off
	s_nop 0
	global_load_dwordx4 v[10:13], v[12:13], off
	s_nop 0
	global_load_dwordx4 v[14:17], v[14:15], off
	v_ashrrev_i32_e32 v187, 6, v76
	v_and_b32_e32 v185, 31, v76
	v_lshlrev_b32_e32 v182, 5, v187
	v_or_b32_e32 v22, v182, v185
	v_ashrrev_i32_e32 v23, 31, v22
	v_bfe_u32 v186, v76, 5, 1
	v_lshlrev_b64 v[22:23], 11, v[22:23]
	v_lshl_add_u64 v[22:23], s[20:21], 0, v[22:23]
	v_lshlrev_b32_e32 v98, 4, v186
	v_lshl_add_u64 v[22:23], v[22:23], 0, v[98:99]
	global_load_dwordx4 v[120:123], v[22:23], off
	global_load_dwordx4 v[112:115], v[22:23], off offset:32
	global_load_dwordx4 v[128:131], v[22:23], off offset:64
	global_load_dwordx4 v[124:127], v[22:23], off offset:96
	global_load_dwordx4 v[116:119], v[22:23], off offset:128
	global_load_dwordx4 v[108:111], v[22:23], off offset:160
	global_load_dwordx4 v[104:107], v[22:23], off offset:192
	global_load_dwordx4 v[100:103], v[22:23], off offset:224
	v_and_b32_e32 v21, 0xfffff0, v18
	v_lshlrev_b32_e32 v26, 1, v18
	v_lshrrev_b32_e32 v27, 1, v18
	v_and_b32_e32 v28, 3, v18
	v_and_or_b32 v21, v26, 8, v21
	v_and_or_b32 v26, v27, 4, v28
	v_and_b32_e32 v27, 0xfffff0, v20
	v_lshlrev_b32_e32 v28, 1, v20
	v_and_b32_e32 v19, 0x70, v76
	v_bfe_u32 v24, v24, 5, 2
	v_lshlrev_b32_e32 v18, 8, v18
	v_lshlrev_b32_e32 v20, 8, v20
	v_lshrrev_b32_e32 v21, 1, v21
	v_and_or_b32 v27, v28, 8, v27
	v_bitop3_b32 v18, v25, v18, v19 bitop3:0xde
	v_bitop3_b32 v19, v25, v20, v19 bitop3:0xde
	v_or_b32_e32 v20, v21, v24
	v_lshrrev_b32_e32 v21, 1, v27
	v_lshlrev_b32_e32 v26, 6, v26
	v_and_b32_e32 v29, 48, v25
	v_add_u32_e32 v193, 0, v18
	v_add_u32_e32 v194, 0, v19
	v_lshlrev_b32_e32 v18, 9, v20
	v_or_b32_e32 v19, v21, v24
	v_or3_b32 v18, v18, v26, v29
	v_lshlrev_b32_e32 v19, 9, v19
	v_lshlrev_b32_e32 v183, 4, v76
	v_or3_b32 v19, v19, v26, v29
	v_add_u32_e32 v195, 0, v18
	v_add_u32_e32 v208, 0, v19
	s_waitcnt vmcnt(0)
	s_add_i32 s9, 0, 0x10000
	s_mov_b64 s[10:11], 0x8000
	v_and_b32_e32 v184, 63, v76
	s_cmp_lg_u32 0, -1
	s_mov_b32 s52, s53
	s_mov_b32 s54, s53
	s_mov_b32 s55, s53
	s_mov_b32 s56, s53
	s_mov_b32 s57, s53
	s_mov_b32 s58, s53
	s_waitcnt vmcnt(0)
	ds_write_b128 v195, v[2:5]
	ds_write_b128 v208, v[6:9]
	ds_write_b128 v193, v[10:13] offset:32768
	ds_write_b128 v194, v[14:17] offset:32768
	v_lshlrev_b32_e32 v14, 8, v185
	v_and_b32_e32 v15, 0x70, v183
	v_bitop3_b32 v2, v98, v14, v15 bitop3:0xde
	v_add_u32_e32 v209, 0, v2
	s_waitcnt lgkmcnt(0)
	s_barrier
	ds_read_b128 v[2:5], v209 offset:32768
	ds_read_b128 v[6:9], v209 offset:40960
	s_waitcnt lgkmcnt(1)
	v_mfma_f32_32x32x16_bf16 v[18:33], v[2:5], v[120:123], 0
	v_or_b32_e32 v2, 32, v98
	v_bitop3_b32 v2, v2, v14, v15 bitop3:0xde
	v_add_u32_e32 v214, 0, v2
	v_lshlrev_b32_e32 v16, 3, v184
	v_and_b32_e32 v17, 0xc0, v183
	s_mov_b32 s59, s53
	s_mov_b32 s60, s53
	s_waitcnt lgkmcnt(0)
	v_mfma_f32_32x32x16_bf16 v[34:49], v[6:9], v[120:123], 0
	ds_read_b128 v[2:5], v214 offset:32768
	ds_read_b128 v[6:9], v214 offset:40960
	s_mov_b32 s61, s53
	s_mov_b32 s62, s53
	s_mov_b32 s63, s53
	s_mov_b32 s64, s53
	s_mov_b32 s65, s53
	s_mov_b32 s66, s53
	s_waitcnt lgkmcnt(1)
	v_mfma_f32_32x32x16_bf16 v[18:33], v[2:5], v[112:115], v[18:33]
	v_or_b32_e32 v2, 64, v98
	v_bitop3_b32 v2, v2, v14, v15 bitop3:0xde
	v_add_u32_e32 v213, 0, v2
	s_mov_b32 s67, s53
	s_mov_b32 s6, 1
	v_cmp_gt_u32_e64 s[40:41], 32, v184
	v_mov_b32_e32 v190, 0
	s_waitcnt lgkmcnt(0)
	v_mfma_f32_32x32x16_bf16 v[34:49], v[6:9], v[112:115], v[34:49]
	ds_read_b128 v[2:5], v213 offset:32768
	ds_read_b128 v[6:9], v213 offset:40960
	s_waitcnt lgkmcnt(1)
	v_mfma_f32_32x32x16_bf16 v[18:33], v[2:5], v[128:131], v[18:33]
	v_or_b32_e32 v2, 0x60, v98
	v_bitop3_b32 v2, v2, v14, v15 bitop3:0xde
	v_add_u32_e32 v212, 0, v2
	s_waitcnt lgkmcnt(0)
	v_mfma_f32_32x32x16_bf16 v[34:49], v[6:9], v[128:131], v[34:49]
	ds_read_b128 v[2:5], v212 offset:32768
	ds_read_b128 v[6:9], v212 offset:40960
	s_waitcnt lgkmcnt(1)
	v_mfma_f32_32x32x16_bf16 v[18:33], v[2:5], v[124:127], v[18:33]
	v_or_b32_e32 v2, 0x80, v98
	v_bitop3_b32 v2, v2, v14, v15 bitop3:0xde
	v_add_u32_e32 v211, 0, v2
	s_waitcnt lgkmcnt(0)
	v_mfma_f32_32x32x16_bf16 v[34:49], v[6:9], v[124:127], v[34:49]
	ds_read_b128 v[2:5], v211 offset:32768
	ds_read_b128 v[6:9], v211 offset:40960
	s_waitcnt lgkmcnt(1)
	v_mfma_f32_32x32x16_bf16 v[18:33], v[2:5], v[116:119], v[18:33]
	v_or_b32_e32 v2, 0xa0, v98
	v_bitop3_b32 v2, v2, v14, v15 bitop3:0xde
	v_add_u32_e32 v210, 0, v2
	ds_read_b128 v[2:5], v210 offset:32768
	s_waitcnt lgkmcnt(1)
	v_mfma_f32_32x32x16_bf16 v[34:49], v[6:9], v[116:119], v[34:49]
	v_and_b32_e32 v6, 0x3fffffc0, v76
	v_lshl_add_u32 v188, v6, 2, s9
	ds_read_b128 v[6:9], v210 offset:40960
	s_cselect_b32 s9, 0, 0
	v_lshl_add_u32 v189, v185, 2, v188
	s_waitcnt lgkmcnt(1)
	v_mfma_f32_32x32x16_bf16 v[18:33], v[2:5], v[108:111], v[18:33]
	v_lshl_add_u64 v[2:3], v[52:53], 0, s[10:11]
	s_mov_b64 s[10:11], 0xc000
	v_lshl_add_u64 v[4:5], s[36:37], 0, v[2:3]
	v_lshl_add_u64 v[10:11], v[52:53], 0, s[10:11]
	v_lshl_add_u64 v[2:3], s[4:5], 0, v[2:3]
	v_lshl_add_u64 v[12:13], s[36:37], 0, v[10:11]
	global_load_dwordx4 v[54:57], v[4:5], off
	global_load_dwordx4 v[58:61], v[12:13], off
	v_lshl_add_u64 v[4:5], s[4:5], 0, v[10:11]
	global_load_dwordx4 v[62:65], v[2:3], off
	global_load_dwordx4 v[66:69], v[4:5], off
	v_or_b32_e32 v2, 0xc0, v98
	v_bitop3_b32 v2, v2, v14, v15 bitop3:0xde
	v_add_u32_e32 v216, 0, v2
	ds_read_b128 v[2:5], v216 offset:32768
	v_lshlrev_b32_e32 v11, 1, v76
	v_and_or_b32 v10, v16, 24, v17
	s_waitcnt lgkmcnt(1)
	v_mfma_f32_32x32x16_bf16 v[34:49], v[6:9], v[108:111], v[34:49]
	v_and_b32_e32 v6, 32, v11
	v_and_b32_e32 v7, 0x100, v16
	v_or3_b32 v77, v10, v6, v7
	ds_read_b128 v[6:9], v216 offset:40960
	s_mov_b64 s[10:11], 0x14000
	v_add_u32_e32 v192, s9, v77
	s_waitcnt lgkmcnt(1)
	v_mfma_f32_32x32x16_bf16 v[18:33], v[2:5], v[104:107], v[18:33]
	v_or_b32_e32 v2, 0xe0, v98
	v_bitop3_b32 v2, v2, v14, v15 bitop3:0xde
	v_add_u32_e32 v215, 0, v2
	ds_read_b128 v[2:5], v215 offset:32768
	ds_read_b128 v[70:73], v215 offset:40960
	s_waitcnt lgkmcnt(2)
	v_mfma_f32_32x32x16_bf16 v[34:49], v[6:9], v[104:107], v[34:49]
	s_waitcnt lgkmcnt(1)
	v_mfma_f32_32x32x16_bf16 v[18:33], v[2:5], v[100:103], v[18:33]
	v_mov_b64_e32 v[2:3], s[52:53]
	v_mov_b64_e32 v[16:17], s[66:67]
	v_mov_b64_e32 v[4:5], s[54:55]
	v_mov_b64_e32 v[6:7], s[56:57]
	v_mov_b64_e32 v[8:9], s[58:59]
	v_mov_b64_e32 v[10:11], s[60:61]
	v_mov_b64_e32 v[12:13], s[62:63]
	s_waitcnt lgkmcnt(0)
	v_mfma_f32_32x32x16_bf16 v[34:49], v[70:73], v[100:103], v[34:49]
	s_nop 2
	v_max_f32_e32 v70, v19, v19
	v_max_f32_e32 v71, v18, v18
	v_max_f32_e32 v70, v71, v70
	v_max3_f32 v70, v70, v20, v21
	v_max3_f32 v70, v70, v22, v23
	v_max3_f32 v70, v70, v24, v25
	v_max3_f32 v70, v70, v26, v27
	v_max3_f32 v70, v70, v28, v29
	v_max3_f32 v70, v70, v30, v31
	v_max3_f32 v70, v70, v32, v33
	v_max3_f32 v70, v70, v34, v35
	v_max3_f32 v70, v70, v36, v37
	v_max3_f32 v70, v70, v38, v39
	v_max3_f32 v70, v70, v40, v41
	v_max3_f32 v70, v70, v42, v43
	v_max3_f32 v70, v70, v44, v45
	v_max3_f32 v70, v70, v46, v47
	v_max3_f32 v78, v70, v48, v49
	v_lshl_add_u64 v[70:71], v[52:53], 0, s[22:23]
	v_lshl_add_u64 v[72:73], s[36:37], 0, v[70:71]
	v_lshl_add_u64 v[52:53], v[52:53], 0, s[10:11]
	v_lshl_add_u64 v[70:71], s[4:5], 0, v[70:71]
	v_lshl_add_u64 v[74:75], s[36:37], 0, v[52:53]
	global_load_dwordx4 v[132:135], v[72:73], off
	global_load_dwordx4 v[140:143], v[74:75], off
	v_lshl_add_u64 v[52:53], s[4:5], 0, v[52:53]
	global_load_dwordx4 v[136:139], v[70:71], off
	global_load_dwordx4 v[144:147], v[52:53], off
	v_mov_b32_e32 v52, v78
	s_nop 1
	v_permlane32_swap_b32_e32 v78, v52
	v_max_f32_e32 v52, v52, v52
	v_max_f32_e32 v53, v78, v78
	v_max_f32_e32 v52, v53, v52
	v_add_f32_e32 v53, 0x7149f2ca, v52
	v_cmp_ge_f32_e32 vcc, s0, v53
	s_cmp_eq_u64 vcc, exec
	v_max_f32_e32 v52, 0xf149f2ca, v52
	s_cselect_b64 vcc, -1, 0
	v_cndmask_b32_e32 v168, v52, v228, vcc
	v_sub_f32_e32 v53, 0xf149f2ca, v52
	v_mul_f32_e32 v52, 0xbe0293ee, v168
	v_fmamk_f32 v18, v18, 0x3e0293ee, v52
	v_exp_f32_e32 v165, v18
	v_fmamk_f32 v18, v19, 0x3e0293ee, v52
	v_exp_f32_e32 v179, v18
	v_fmamk_f32 v18, v20, 0x3e0293ee, v52
	v_exp_f32_e32 v166, v18
	v_fmamk_f32 v18, v21, 0x3e0293ee, v52
	v_exp_f32_e32 v221, v18
	v_fmamk_f32 v18, v22, 0x3e0293ee, v52
	v_exp_f32_e32 v178, v18
	v_fmamk_f32 v18, v23, 0x3e0293ee, v52
	v_exp_f32_e32 v231, v18
	v_fmamk_f32 v18, v24, 0x3e0293ee, v52
	v_exp_f32_e32 v167, v18
	v_fmamk_f32 v18, v25, 0x3e0293ee, v52
	v_exp_f32_e32 v177, v18
	v_fmamk_f32 v18, v26, 0x3e0293ee, v52
	v_mul_f32_e32 v53, 0x3e0293ee, v53
	v_exp_f32_e32 v173, v18
	v_fmamk_f32 v18, v27, 0x3e0293ee, v52
	v_exp_f32_e32 v53, v53
	v_exp_f32_e32 v175, v18
	v_fmamk_f32 v18, v28, 0x3e0293ee, v52
	v_exp_f32_e32 v174, v18
	v_fmamk_f32 v18, v29, 0x3e0293ee, v52
	v_exp_f32_e32 v176, v18
	v_fmamk_f32 v18, v30, 0x3e0293ee, v52
	v_exp_f32_e32 v169, v18
	v_fmamk_f32 v18, v31, 0x3e0293ee, v52
	v_pk_fma_f32 v[148:149], v[48:49], s[26:27], v[52:53] op_sel_hi:[1,0,0]
	v_pk_fma_f32 v[154:155], v[46:47], s[26:27], v[52:53] op_sel_hi:[1,0,0]
	v_pk_fma_f32 v[158:159], v[44:45], s[26:27], v[52:53] op_sel_hi:[1,0,0]
	v_pk_fma_f32 v[150:151], v[42:43], s[26:27], v[52:53] op_sel_hi:[1,0,0]
	v_pk_fma_f32 v[152:153], v[40:41], s[26:27], v[52:53] op_sel_hi:[1,0,0]
	v_pk_fma_f32 v[156:157], v[38:39], s[26:27], v[52:53] op_sel_hi:[1,0,0]
	v_pk_fma_f32 v[160:161], v[36:37], s[26:27], v[52:53] op_sel_hi:[1,0,0]
	v_pk_fma_f32 v[162:163], v[34:35], s[26:27], v[52:53] op_sel_hi:[1,0,0]
	v_exp_f32_e32 v171, v18
	v_fmamk_f32 v18, v32, 0x3e0293ee, v52
	v_fmac_f32_e32 v52, 0x3e0293ee, v33
	v_and_b32_e32 v20, 15, v76
	v_exp_f32_e32 v170, v18
	v_exp_f32_e32 v172, v52
	v_mad_u64_u32 v[18:19], s[4:5], s7, v229, v[50:51]
	v_lshlrev_b32_e32 v20, 4, v20
	s_waitcnt vmcnt(4)
	v_or3_b32 v18, v18, s8, v20
	v_mov_b64_e32 v[14:15], s[64:65]
	s_waitcnt vmcnt(7)
	ds_write_b128 v195, v[54:57] offset:16384
	s_waitcnt vmcnt(6)
	ds_write_b128 v208, v[58:61] offset:16384
	s_waitcnt vmcnt(5)
	ds_write_b128 v193, v[62:65] offset:49152
	s_waitcnt vmcnt(4)
	ds_write_b128 v194, v[66:69] offset:49152
	v_cndmask_b32_e64 v217, v53, 1.0, vcc
	s_addk_i32 s9, 0x4000
	v_lshl_add_u64 v[180:181], s[46:47], 0, v[18:19]
	v_mov_b64_e32 v[64:65], v[16:17]
	v_mov_b64_e32 v[48:49], v[16:17]
	v_mov_b64_e32 v[32:33], v[16:17]
	v_add_u32_e32 v191, s9, v77
	v_mov_b64_e32 v[62:63], v[14:15]
	v_mov_b64_e32 v[60:61], v[12:13]
	v_mov_b64_e32 v[58:59], v[10:11]
	v_mov_b64_e32 v[56:57], v[8:9]
	v_mov_b64_e32 v[54:55], v[6:7]
	v_mov_b64_e32 v[52:53], v[4:5]
	v_mov_b64_e32 v[50:51], v[2:3]
	v_mov_b64_e32 v[46:47], v[14:15]
	v_mov_b64_e32 v[44:45], v[12:13]
	v_mov_b64_e32 v[42:43], v[10:11]
	v_mov_b64_e32 v[40:41], v[8:9]
	v_mov_b64_e32 v[38:39], v[6:7]
	v_mov_b64_e32 v[36:37], v[4:5]
	v_mov_b64_e32 v[34:35], v[2:3]
	v_mov_b64_e32 v[30:31], v[14:15]
	v_mov_b64_e32 v[28:29], v[12:13]
	v_mov_b64_e32 v[26:27], v[10:11]
	v_mov_b64_e32 v[24:25], v[8:9]
	v_mov_b64_e32 v[22:23], v[6:7]
	v_mov_b64_e32 v[20:21], v[4:5]
	v_mov_b64_e32 v[18:19], v[2:3]
	s_waitcnt lgkmcnt(0)
	s_barrier
	.p2align	6

.LBB0_704:
	s_xor_b64 s[62:63], s[56:57], -1
	s_add_i32 s89, s7, -2
	s_add_u32 s90, s36, 0x10000
	v_mov_b32_e32 v2, 0
	s_mov_b64 s[56:57], s[20:21]
	s_addc_u32 s91, s37, 0
	s_mov_b32 s10, 0
	v_mov_b32_e32 v3, v2
	v_mov_b32_e32 v4, v2
	v_mov_b32_e32 v5, v2
	v_mov_b32_e32 v6, v2
	v_mov_b32_e32 v7, v2
	v_mov_b32_e32 v8, v2
	v_mov_b32_e32 v9, v2
	v_mov_b32_e32 v18, v2
	v_mov_b32_e32 v19, v2
	v_mov_b32_e32 v20, v2
	v_mov_b32_e32 v21, v2
	v_mov_b32_e32 v22, v2
	v_mov_b32_e32 v23, v2
	v_mov_b32_e32 v24, v2
	v_mov_b32_e32 v25, v2
	v_mov_b32_e32 v34, v2
	v_mov_b32_e32 v35, v2
	v_mov_b32_e32 v36, v2
	v_mov_b32_e32 v37, v2
	v_mov_b32_e32 v38, v2
	v_mov_b32_e32 v39, v2
	v_mov_b32_e32 v40, v2
	v_mov_b32_e32 v41, v2
	v_mov_b32_e32 v58, v2
	v_mov_b32_e32 v59, v2
	v_mov_b32_e32 v60, v2
	v_mov_b32_e32 v61, v2
	v_mov_b32_e32 v62, v2
	v_mov_b32_e32 v63, v2
	v_mov_b32_e32 v64, v2
	v_mov_b32_e32 v65, v2
	v_mov_b32_e32 v10, v2
	v_mov_b32_e32 v11, v2
	v_mov_b32_e32 v12, v2
	v_mov_b32_e32 v13, v2
	v_mov_b32_e32 v14, v2
	v_mov_b32_e32 v15, v2
	v_mov_b32_e32 v16, v2
	v_mov_b32_e32 v17, v2
	v_mov_b32_e32 v26, v2
	v_mov_b32_e32 v27, v2
	v_mov_b32_e32 v28, v2
	v_mov_b32_e32 v29, v2
	v_mov_b32_e32 v30, v2
	v_mov_b32_e32 v31, v2
	v_mov_b32_e32 v32, v2
	v_mov_b32_e32 v33, v2
	v_mov_b32_e32 v42, v2
	v_mov_b32_e32 v43, v2
	v_mov_b32_e32 v44, v2
	v_mov_b32_e32 v45, v2
	v_mov_b32_e32 v46, v2
	v_mov_b32_e32 v47, v2
	v_mov_b32_e32 v48, v2
	v_mov_b32_e32 v49, v2
	v_mov_b32_e32 v74, v2
	v_mov_b32_e32 v75, v2
	v_mov_b32_e32 v76, v2
	v_mov_b32_e32 v77, v2
	v_mov_b32_e32 v78, v2
	v_mov_b32_e32 v79, v2
	v_mov_b32_e32 v80, v2
	v_mov_b32_e32 v81, v2
	v_mov_b32_e32 v82, v2
	v_mov_b32_e32 v83, v2
	v_mov_b32_e32 v84, v2
	v_mov_b32_e32 v85, v2
	v_mov_b32_e32 v86, v2
	v_mov_b32_e32 v87, v2
	v_mov_b32_e32 v88, v2
	v_mov_b32_e32 v89, v2
	v_mov_b32_e32 v100, v2
	v_mov_b32_e32 v101, v2
	v_mov_b32_e32 v102, v2
	v_mov_b32_e32 v103, v2
	v_mov_b32_e32 v104, v2
	v_mov_b32_e32 v105, v2
	v_mov_b32_e32 v106, v2
	v_mov_b32_e32 v107, v2
	v_mov_b32_e32 v116, v2
	v_mov_b32_e32 v117, v2
	v_mov_b32_e32 v118, v2
	v_mov_b32_e32 v119, v2
	v_mov_b32_e32 v120, v2
	v_mov_b32_e32 v121, v2
	v_mov_b32_e32 v122, v2
	v_mov_b32_e32 v123, v2
	v_mov_b32_e32 v132, v2
	v_mov_b32_e32 v133, v2
	v_mov_b32_e32 v134, v2
	v_mov_b32_e32 v135, v2
	v_mov_b32_e32 v136, v2
	v_mov_b32_e32 v137, v2
	v_mov_b32_e32 v138, v2
	v_mov_b32_e32 v139, v2
	v_mov_b32_e32 v90, v2
	v_mov_b32_e32 v91, v2
	v_mov_b32_e32 v92, v2
	v_mov_b32_e32 v93, v2
	v_mov_b32_e32 v94, v2
	v_mov_b32_e32 v95, v2
	v_mov_b32_e32 v96, v2
	v_mov_b32_e32 v97, v2
	v_mov_b32_e32 v108, v2
	v_mov_b32_e32 v109, v2
	v_mov_b32_e32 v110, v2
	v_mov_b32_e32 v111, v2
	v_mov_b32_e32 v112, v2
	v_mov_b32_e32 v113, v2
	v_mov_b32_e32 v114, v2
	v_mov_b32_e32 v115, v2
	v_mov_b32_e32 v124, v2
	v_mov_b32_e32 v125, v2
	v_mov_b32_e32 v126, v2
	v_mov_b32_e32 v127, v2
	v_mov_b32_e32 v128, v2
	v_mov_b32_e32 v129, v2
	v_mov_b32_e32 v130, v2
	v_mov_b32_e32 v131, v2
	v_mov_b32_e32 v140, v2
	v_mov_b32_e32 v141, v2
	v_mov_b32_e32 v142, v2
	v_mov_b32_e32 v143, v2
	v_mov_b32_e32 v144, v2
	v_mov_b32_e32 v145, v2
	v_mov_b32_e32 v146, v2
	v_mov_b32_e32 v147, v2
	s_cmp_eq_u32 s100, 1
	s_cbranch_scc1 .Lgo_h0_loop
	s_cmp_eq_u32 s100, 2
	s_cbranch_scc1 .Lgo_h1_loop
	.p2align	6

.LBB0_975:
	s_ashr_i32 s73, s72, 31
	s_lshl_b64 s[10:11], s[72:73], 20
	s_add_u32 s20, s84, s10
	s_addc_u32 s21, s85, s11
	s_and_b64 s[10:11], s[44:45], exec
	s_cselect_b32 s9, s21, s5
	s_cselect_b32 s47, s20, s4
	s_ashr_i32 s71, s70, 31
	s_lshl_b64 s[10:11], s[70:71], 20
	s_add_u32 s74, s86, s10
	s_addc_u32 s75, s87, s11
	s_and_b64 s[10:11], s[44:45], exec
	s_cselect_b32 s71, s75, s49
	s_cselect_b32 s73, s74, s48
	s_add_u32 s76, s48, 0x10000
	s_addc_u32 s77, s49, 0
	s_add_u32 s48, s4, 0x80080
	v_mov_b32_e32 v108, 0
	s_addc_u32 s49, s5, 0
	s_mov_b32 s10, -2
	v_mov_b32_e32 v109, v108
	v_mov_b32_e32 v110, v108
	v_mov_b32_e32 v111, v108
	v_mov_b32_e32 v104, v108
	v_mov_b32_e32 v105, v108
	v_mov_b32_e32 v106, v108
	v_mov_b32_e32 v107, v108
	v_mov_b32_e32 v74, v108
	v_mov_b32_e32 v75, v108
	v_mov_b32_e32 v76, v108
	v_mov_b32_e32 v77, v108
	v_mov_b32_e32 v66, v108
	v_mov_b32_e32 v67, v108
	v_mov_b32_e32 v68, v108
	v_mov_b32_e32 v69, v108
	v_mov_b32_e32 v132, v108
	v_mov_b32_e32 v133, v108
	v_mov_b32_e32 v134, v108
	v_mov_b32_e32 v135, v108
	v_mov_b32_e32 v54, v108
	v_mov_b32_e32 v55, v108
	v_mov_b32_e32 v56, v108
	v_mov_b32_e32 v57, v108
	v_mov_b32_e32 v50, v108
	v_mov_b32_e32 v51, v108
	v_mov_b32_e32 v52, v108
	v_mov_b32_e32 v53, v108
	v_mov_b32_e32 v14, v108
	v_mov_b32_e32 v15, v108
	v_mov_b32_e32 v16, v108
	v_mov_b32_e32 v17, v108
	v_mov_b32_e32 v10, v108
	v_mov_b32_e32 v11, v108
	v_mov_b32_e32 v12, v108
	v_mov_b32_e32 v13, v108
	v_mov_b32_e32 v2, v108
	v_mov_b32_e32 v3, v108
	v_mov_b32_e32 v4, v108
	v_mov_b32_e32 v5, v108
	v_mov_b32_e32 v6, v108
	v_mov_b32_e32 v7, v108
	v_mov_b32_e32 v8, v108
	v_mov_b32_e32 v9, v108
	v_mov_b32_e32 v26, v108
	v_mov_b32_e32 v27, v108
	v_mov_b32_e32 v28, v108
	v_mov_b32_e32 v29, v108
	v_mov_b32_e32 v30, v108
	v_mov_b32_e32 v31, v108
	v_mov_b32_e32 v32, v108
	v_mov_b32_e32 v33, v108
	v_mov_b32_e32 v42, v108
	v_mov_b32_e32 v43, v108
	v_mov_b32_e32 v44, v108
	v_mov_b32_e32 v45, v108
	v_mov_b32_e32 v46, v108
	v_mov_b32_e32 v47, v108
	v_mov_b32_e32 v48, v108
	v_mov_b32_e32 v49, v108
	v_mov_b32_e32 v58, v108
	v_mov_b32_e32 v59, v108
	v_mov_b32_e32 v60, v108
	v_mov_b32_e32 v61, v108
	v_mov_b32_e32 v62, v108
	v_mov_b32_e32 v63, v108
	v_mov_b32_e32 v64, v108
	v_mov_b32_e32 v65, v108
	v_mov_b32_e32 v18, v108
	v_mov_b32_e32 v19, v108
	v_mov_b32_e32 v20, v108
	v_mov_b32_e32 v21, v108
	v_mov_b32_e32 v22, v108
	v_mov_b32_e32 v23, v108
	v_mov_b32_e32 v24, v108
	v_mov_b32_e32 v25, v108
	v_mov_b32_e32 v34, v108
	v_mov_b32_e32 v35, v108
	v_mov_b32_e32 v36, v108
	v_mov_b32_e32 v37, v108
	v_mov_b32_e32 v38, v108
	v_mov_b32_e32 v39, v108
	v_mov_b32_e32 v40, v108
	v_mov_b32_e32 v41, v108
	v_mov_b32_e32 v70, v108
	v_mov_b32_e32 v71, v108
	v_mov_b32_e32 v72, v108
	v_mov_b32_e32 v73, v108
	v_mov_b32_e32 v78, v108
	v_mov_b32_e32 v79, v108
	v_mov_b32_e32 v80, v108
	v_mov_b32_e32 v81, v108
	v_mov_b32_e32 v90, v108
	v_mov_b32_e32 v91, v108
	v_mov_b32_e32 v92, v108
	v_mov_b32_e32 v93, v108
	v_mov_b32_e32 v94, v108
	v_mov_b32_e32 v95, v108
	v_mov_b32_e32 v96, v108
	v_mov_b32_e32 v97, v108
	v_mov_b32_e32 v116, v108
	v_mov_b32_e32 v117, v108
	v_mov_b32_e32 v118, v108
	v_mov_b32_e32 v119, v108
	v_mov_b32_e32 v124, v108
	v_mov_b32_e32 v125, v108
	v_mov_b32_e32 v126, v108
	v_mov_b32_e32 v127, v108
	v_mov_b32_e32 v160, v108
	v_mov_b32_e32 v161, v108
	v_mov_b32_e32 v162, v108
	v_mov_b32_e32 v163, v108
	v_mov_b32_e32 v82, v108
	v_mov_b32_e32 v83, v108
	v_mov_b32_e32 v84, v108
	v_mov_b32_e32 v85, v108
	v_mov_b32_e32 v86, v108
	v_mov_b32_e32 v87, v108
	v_mov_b32_e32 v88, v108
	v_mov_b32_e32 v89, v108
	v_mov_b32_e32 v100, v108
	v_mov_b32_e32 v101, v108
	v_mov_b32_e32 v102, v108
	v_mov_b32_e32 v103, v108
	v_mov_b32_e32 v112, v108
	v_mov_b32_e32 v113, v108
	v_mov_b32_e32 v114, v108
	v_mov_b32_e32 v115, v108
	.p2align	6

.LBB0_1161:
	s_xor_b64 s[56:57], s[46:47], -1
	s_add_i32 s84, s6, -2
	s_add_u32 s85, s36, 0x10000
	v_mov_b32_e32 v2, 0
	s_mov_b64 s[46:47], s[20:21]
	s_addc_u32 s86, s37, 0
	s_mov_b32 s10, 0
	v_mov_b32_e32 v3, v2
	v_mov_b32_e32 v4, v2
	v_mov_b32_e32 v5, v2
	v_mov_b32_e32 v6, v2
	v_mov_b32_e32 v7, v2
	v_mov_b32_e32 v8, v2
	v_mov_b32_e32 v9, v2
	v_mov_b32_e32 v18, v2
	v_mov_b32_e32 v19, v2
	v_mov_b32_e32 v20, v2
	v_mov_b32_e32 v21, v2
	v_mov_b32_e32 v22, v2
	v_mov_b32_e32 v23, v2
	v_mov_b32_e32 v24, v2
	v_mov_b32_e32 v25, v2
	v_mov_b32_e32 v34, v2
	v_mov_b32_e32 v35, v2
	v_mov_b32_e32 v36, v2
	v_mov_b32_e32 v37, v2
	v_mov_b32_e32 v38, v2
	v_mov_b32_e32 v39, v2
	v_mov_b32_e32 v40, v2
	v_mov_b32_e32 v41, v2
	v_mov_b32_e32 v50, v2
	v_mov_b32_e32 v51, v2
	v_mov_b32_e32 v52, v2
	v_mov_b32_e32 v53, v2
	v_mov_b32_e32 v54, v2
	v_mov_b32_e32 v55, v2
	v_mov_b32_e32 v56, v2
	v_mov_b32_e32 v57, v2
	v_mov_b32_e32 v10, v2
	v_mov_b32_e32 v11, v2
	v_mov_b32_e32 v12, v2
	v_mov_b32_e32 v13, v2
	v_mov_b32_e32 v14, v2
	v_mov_b32_e32 v15, v2
	v_mov_b32_e32 v16, v2
	v_mov_b32_e32 v17, v2
	v_mov_b32_e32 v26, v2
	v_mov_b32_e32 v27, v2
	v_mov_b32_e32 v28, v2
	v_mov_b32_e32 v29, v2
	v_mov_b32_e32 v30, v2
	v_mov_b32_e32 v31, v2
	v_mov_b32_e32 v32, v2
	v_mov_b32_e32 v33, v2
	v_mov_b32_e32 v42, v2
	v_mov_b32_e32 v43, v2
	v_mov_b32_e32 v44, v2
	v_mov_b32_e32 v45, v2
	v_mov_b32_e32 v46, v2
	v_mov_b32_e32 v47, v2
	v_mov_b32_e32 v48, v2
	v_mov_b32_e32 v49, v2
	v_mov_b32_e32 v58, v2
	v_mov_b32_e32 v59, v2
	v_mov_b32_e32 v60, v2
	v_mov_b32_e32 v61, v2
	v_mov_b32_e32 v62, v2
	v_mov_b32_e32 v63, v2
	v_mov_b32_e32 v64, v2
	v_mov_b32_e32 v65, v2
	v_mov_b32_e32 v74, v2
	v_mov_b32_e32 v75, v2
	v_mov_b32_e32 v76, v2
	v_mov_b32_e32 v77, v2
	v_mov_b32_e32 v78, v2
	v_mov_b32_e32 v79, v2
	v_mov_b32_e32 v80, v2
	v_mov_b32_e32 v81, v2
	v_mov_b32_e32 v100, v2
	v_mov_b32_e32 v101, v2
	v_mov_b32_e32 v102, v2
	v_mov_b32_e32 v103, v2
	v_mov_b32_e32 v104, v2
	v_mov_b32_e32 v105, v2
	v_mov_b32_e32 v106, v2
	v_mov_b32_e32 v107, v2
	v_mov_b32_e32 v116, v2
	v_mov_b32_e32 v117, v2
	v_mov_b32_e32 v118, v2
	v_mov_b32_e32 v119, v2
	v_mov_b32_e32 v120, v2
	v_mov_b32_e32 v121, v2
	v_mov_b32_e32 v122, v2
	v_mov_b32_e32 v123, v2
	v_mov_b32_e32 v132, v2
	v_mov_b32_e32 v133, v2
	v_mov_b32_e32 v134, v2
	v_mov_b32_e32 v135, v2
	v_mov_b32_e32 v136, v2
	v_mov_b32_e32 v137, v2
	v_mov_b32_e32 v138, v2
	v_mov_b32_e32 v139, v2
	v_mov_b32_e32 v90, v2
	v_mov_b32_e32 v91, v2
	v_mov_b32_e32 v92, v2
	v_mov_b32_e32 v93, v2
	v_mov_b32_e32 v94, v2
	v_mov_b32_e32 v95, v2
	v_mov_b32_e32 v96, v2
	v_mov_b32_e32 v97, v2
	v_mov_b32_e32 v108, v2
	v_mov_b32_e32 v109, v2
	v_mov_b32_e32 v110, v2
	v_mov_b32_e32 v111, v2
	v_mov_b32_e32 v112, v2
	v_mov_b32_e32 v113, v2
	v_mov_b32_e32 v114, v2
	v_mov_b32_e32 v115, v2
	v_mov_b32_e32 v124, v2
	v_mov_b32_e32 v125, v2
	v_mov_b32_e32 v126, v2
	v_mov_b32_e32 v127, v2
	v_mov_b32_e32 v128, v2
	v_mov_b32_e32 v129, v2
	v_mov_b32_e32 v130, v2
	v_mov_b32_e32 v131, v2
	v_mov_b32_e32 v140, v2
	v_mov_b32_e32 v141, v2
	v_mov_b32_e32 v142, v2
	v_mov_b32_e32 v143, v2
	v_mov_b32_e32 v144, v2
	v_mov_b32_e32 v145, v2
	v_mov_b32_e32 v146, v2
	v_mov_b32_e32 v147, v2
	s_cmp_eq_u32 s100, 1
	s_cbranch_scc1 .Lgd_h0_loop
	s_cmp_eq_u32 s100, 2
	s_cbranch_scc1 .Lgd_h1_loop
	.p2align	6
